# attention cross-half max via v_permlane32_swap instead of ds_bpermute; on top of previous de-serialisation patches
# baseline (speedup 1.0000x reference)
; #define LAS __attribute__((address_space(3)))
; __device__ __forceinline__ void softmax_pv(f32x16& s0, f32x16& s1, float& mrun, float& lsum, f32x16 (&o)[2], const LAS unsigned char* Vt, int r32, int hi) {
;     float mt = max16(s0, s1); mt = fmaxf(mt, __shfl_xor(mt, 32));
;     const float mnew = fmaxf(mrun, mt), msafe = (mnew == -INFINITY) ? 0.f : mnew;
;     const float alpha = __builtin_amdgcn_exp2f(mrun - msafe);
;     typedef float f32x2v __attribute__((ext_vector_type(2)));
;     const f32x2v mm = {msafe, msafe}; f32x2v ps2 = {0.f, 0.f};
; #pragma unroll
;     for (int r = 0; r < 16; r += 2) {
;         f32x2v d0 = (f32x2v){s0[r], s0[r + 1]} - mm, d1 = (f32x2v){s1[r], s1[r + 1]} - mm;
;         s0[r] = __builtin_amdgcn_exp2f(d0[0]); s0[r + 1] = __builtin_amdgcn_exp2f(d0[1]); s1[r] = __builtin_amdgcn_exp2f(d1[0]); s1[r + 1] = __builtin_amdgcn_exp2f(d1[1]);
;         ps2 += (f32x2v){s0[r], s0[r + 1]}; ps2 += (f32x2v){s1[r], s1[r + 1]}; }
;     lsum = lsum * alpha + (ps2[0] + ps2[1]); mrun = mnew;
; #pragma unroll
;     for (int r = 0; r < 16; ++r) { o[0][r] *= alpha; o[1][r] *= alpha; }
;     pv_tile(o, Vt, s0, s1, r32, hi);
; template <int MODE> ...
;     ...
;         if (more) { LAS unsigned char* Kn = tb + (cur ^ 1) * 2 * TILEB; tile_st(Kn, kw, tid); tile_st(Kn + TILEB, vw, tid); }
.LBB0_850:
	v_max3_f32 v1, v119, v69, v86
	v_max3_f32 v70, v114, v84, v115
	v_max3_f32 v1, v1, v72, v87
	v_max3_f32 v70, v70, v85, v94
	v_max3_f32 v1, v1, v73, v68
	v_max3_f32 v70, v70, v88, v95
	v_max3_f32 v1, v1, v118, v116
	v_max3_f32 v70, v70, v89, v96
	v_max3_f32 v1, v1, v76, v117
	v_max3_f32 v70, v70, v92, v97
	v_max3_f32 v1, v1, v77, v90
	v_max3_f32 v70, v70, v93, v98
	v_max3_f32 v1, v1, v80, v91
	v_max3_f32 v70, v70, v112, v99
	v_max3_f32 v1, v1, v81, v113
	v_max_f32_e32 v1, v1, v70
	v_mov_b32_e32 v70, v1
	v_mov_b32_e32 v71, v1
	s_nop 1
	v_permlane32_swap_b32_e32 v70, v71
	v_max3_f32 v120, v170, v70, v71
	v_cmp_neq_f32_e32 vcc, s96, v120
	s_nop 1
	v_cndmask_b32_e32 v122, 0, v120, vcc
	v_sub_f32_e32 v1, v170, v122
	v_pk_add_f32 v[68:69], v[68:69], v[122:123] op_sel_hi:[1,0] neg_lo:[0,1] neg_hi:[0,1]
	v_pk_add_f32 v[72:73], v[72:73], v[122:123] op_sel_hi:[1,0] neg_lo:[0,1] neg_hi:[0,1]
	v_pk_add_f32 v[76:77], v[76:77], v[122:123] op_sel_hi:[1,0] neg_lo:[0,1] neg_hi:[0,1]
	v_pk_add_f32 v[80:81], v[80:81], v[122:123] op_sel_hi:[1,0] neg_lo:[0,1] neg_hi:[0,1]
	v_exp_f32_e32 v68, v68
	v_exp_f32_e32 v69, v69
	v_exp_f32_e32 v72, v72
	v_exp_f32_e32 v73, v73
	v_exp_f32_e32 v76, v76
	v_exp_f32_e32 v77, v77
	v_pk_add_f32 v[82:83], v[90:91], v[122:123] op_sel_hi:[1,0] neg_lo:[0,1] neg_hi:[0,1]
	v_exp_f32_e32 v80, v80
	v_exp_f32_e32 v81, v81
	v_pk_add_f32 v[90:91], v[94:95], v[122:123] op_sel_hi:[1,0] neg_lo:[0,1] neg_hi:[0,1]
	v_pk_add_f32 v[94:95], v[96:97], v[122:123] op_sel_hi:[1,0] neg_lo:[0,1] neg_hi:[0,1]
	v_pk_add_f32 v[96:97], v[112:113], v[122:123] op_sel_hi:[1,0] neg_lo:[0,1] neg_hi:[0,1]
	v_exp_f32_e32 v112, v1
	v_add3_u32 v1, s13, v124, v237
	v_pk_add_f32 v[70:71], v[118:119], v[122:123] op_sel_hi:[1,0] neg_lo:[0,1] neg_hi:[0,1]
	v_pk_add_f32 v[74:75], v[86:87], v[122:123] op_sel_hi:[1,0] neg_lo:[0,1] neg_hi:[0,1]
	v_pk_add_f32 v[78:79], v[116:117], v[122:123] op_sel_hi:[1,0] neg_lo:[0,1] neg_hi:[0,1]
	v_pk_add_f32 v[84:85], v[84:85], v[122:123] op_sel_hi:[1,0] neg_lo:[0,1] neg_hi:[0,1]
	v_pk_add_f32 v[86:87], v[114:115], v[122:123] op_sel_hi:[1,0] neg_lo:[0,1] neg_hi:[0,1]
	v_pk_add_f32 v[88:89], v[88:89], v[122:123] op_sel_hi:[1,0] neg_lo:[0,1] neg_hi:[0,1]
	v_pk_add_f32 v[92:93], v[92:93], v[122:123] op_sel_hi:[1,0] neg_lo:[0,1] neg_hi:[0,1]
	v_pk_add_f32 v[98:99], v[98:99], v[122:123] op_sel_hi:[1,0] neg_lo:[0,1] neg_hi:[0,1]
	ds_read_b128 v[122:125], v1 offset:9216
	ds_read_b128 v[126:129], v1 offset:9248
	v_pk_mul_f32 v[66:67], v[66:67], v[112:113] op_sel_hi:[1,0]
	v_pk_mul_f32 v[64:65], v[64:65], v[112:113] op_sel_hi:[1,0]
	v_pk_mul_f32 v[62:63], v[62:63], v[112:113] op_sel_hi:[1,0]
	v_pk_mul_f32 v[60:61], v[60:61], v[112:113] op_sel_hi:[1,0]
	v_pk_mul_f32 v[58:59], v[58:59], v[112:113] op_sel_hi:[1,0]
	v_pk_mul_f32 v[56:57], v[56:57], v[112:113] op_sel_hi:[1,0]
	v_pk_mul_f32 v[54:55], v[54:55], v[112:113] op_sel_hi:[1,0]
	v_pk_mul_f32 v[52:53], v[52:53], v[112:113] op_sel_hi:[1,0]
	v_cvt_pk_bf16_f32 v114, v68, v69
	v_cvt_pk_bf16_f32 v115, v72, v73
	v_cvt_pk_bf16_f32 v116, v76, v77
	v_cvt_pk_bf16_f32 v117, v80, v81
	v_pk_mul_f32 v[50:51], v[50:51], v[112:113] op_sel_hi:[1,0]
	v_pk_mul_f32 v[48:49], v[48:49], v[112:113] op_sel_hi:[1,0]
	s_waitcnt lgkmcnt(1)
	v_mfma_f32_32x32x16_bf16 v[52:67], v[122:125], v[114:117], v[52:67]
	ds_read_b128 v[122:125], v1 offset:13824
	v_mul_f32_e64 v46, v46, v112
	v_mul_f32_e64 v47, v47, v112
	v_mul_f32_e64 v44, v44, v112
	v_mul_f32_e64 v45, v45, v112
	v_pk_mul_f32 v[42:43], v[42:43], v[112:113] op_sel_hi:[1,0]
	v_pk_mul_f32 v[40:41], v[40:41], v[112:113] op_sel_hi:[1,0]
	v_pk_mul_f32 v[38:39], v[38:39], v[112:113] op_sel_hi:[1,0]
	v_pk_mul_f32 v[36:37], v[36:37], v[112:113] op_sel_hi:[1,0]
	v_exp_f32_e32 v84, v84
	v_exp_f32_e32 v85, v85
	s_waitcnt lgkmcnt(0)
	v_mfma_f32_32x32x16_bf16 v[36:51], v[122:125], v[114:117], v[36:51]
	ds_read_b128 v[122:125], v1 offset:13856
	v_exp_f32_e32 v88, v88
	v_exp_f32_e32 v89, v89
	v_exp_f32_e32 v92, v92
	v_exp_f32_e32 v93, v93
	v_exp_f32_e32 v96, v96
	v_exp_f32_e32 v97, v97
	v_cvt_pk_bf16_f32 v114, v84, v85
	v_cvt_pk_bf16_f32 v115, v88, v89
	v_cvt_pk_bf16_f32 v116, v92, v93
	v_cvt_pk_bf16_f32 v117, v96, v97
	v_exp_f32_e32 v70, v70
	v_exp_f32_e32 v71, v71
	s_waitcnt lgkmcnt(0)
	v_mfma_f32_32x32x16_bf16 v[36:51], v[122:125], v[114:117], v[36:51]
	ds_read_b128 v[122:125], v1 offset:9280
	v_exp_f32_e32 v74, v74
	v_exp_f32_e32 v75, v75
	v_exp_f32_e32 v78, v78
	v_exp_f32_e32 v79, v79
	v_exp_f32_e32 v82, v82
	v_exp_f32_e32 v83, v83
	v_mfma_f32_32x32x16_bf16 v[52:67], v[126:129], v[114:117], v[52:67]
	v_cvt_pk_bf16_f32 v114, v70, v71
	v_cvt_pk_bf16_f32 v115, v74, v75
	v_cvt_pk_bf16_f32 v116, v78, v79
	v_cvt_pk_bf16_f32 v117, v82, v83
	v_exp_f32_e32 v86, v86
	v_exp_f32_e32 v87, v87
	v_exp_f32_e32 v90, v90
	s_waitcnt lgkmcnt(0)
	v_mfma_f32_32x32x16_bf16 v[52:67], v[122:125], v[114:117], v[52:67]
	ds_read_b128 v[122:125], v1 offset:13888
	v_exp_f32_e32 v91, v91
	v_exp_f32_e32 v94, v94
	v_exp_f32_e32 v95, v95
	v_exp_f32_e32 v98, v98
	v_exp_f32_e32 v99, v99
	s_andn2_b64 vcc, exec, s[10:11]
	s_waitcnt lgkmcnt(0)
	v_mfma_f32_32x32x16_bf16 v[36:51], v[122:125], v[114:117], v[36:51]
	ds_read_b128 v[122:125], v1 offset:9312
	v_cvt_pk_bf16_f32 v114, v86, v87
	v_cvt_pk_bf16_f32 v115, v90, v91
	v_cvt_pk_bf16_f32 v116, v94, v95
	v_cvt_pk_bf16_f32 v117, v98, v99
	s_waitcnt lgkmcnt(0)
	s_nop 0
	v_mfma_f32_32x32x16_bf16 v[52:67], v[122:125], v[114:117], v[52:67]
	ds_read_b128 v[122:125], v1 offset:13920
	s_waitcnt lgkmcnt(0)
	v_mfma_f32_32x32x16_bf16 v[36:51], v[122:125], v[114:117], v[36:51]
	s_cbranch_vccnz .LBB0_852
	s_lshl_b32 s4, s12, 1
	s_xor_b32 s4, s4, 2
	s_mulk_i32 s4, 0x2400
	v_add_u32_e32 v1, s4, v157
	s_waitcnt vmcnt(1)
	ds_write_b128 v1, v[100:103]
	s_waitcnt vmcnt(0)
	ds_write_b128 v1, v[104:107] offset:9216

; #define LAS __attribute__((address_space(3)))
; __device__ __forceinline__ void softmax_pv(f32x16& s0, f32x16& s1, float& mrun, float& lsum, f32x16 (&o)[2], const LAS unsigned char* Vt, int r32, int hi) {
;     float mt = max16(s0, s1); mt = fmaxf(mt, __shfl_xor(mt, 32));
;     const float mnew = fmaxf(mrun, mt), msafe = (mnew == -INFINITY) ? 0.f : mnew;
;     const float alpha = __builtin_amdgcn_exp2f(mrun - msafe);
;     typedef float f32x2v __attribute__((ext_vector_type(2)));
;     const f32x2v mm = {msafe, msafe}; f32x2v ps2 = {0.f, 0.f};
; #pragma unroll
;     for (int r = 0; r < 16; r += 2) {
;         f32x2v d0 = (f32x2v){s0[r], s0[r + 1]} - mm, d1 = (f32x2v){s1[r], s1[r + 1]} - mm;
;         s0[r] = __builtin_amdgcn_exp2f(d0[0]); s0[r + 1] = __builtin_amdgcn_exp2f(d0[1]); s1[r] = __builtin_amdgcn_exp2f(d1[0]); s1[r + 1] = __builtin_amdgcn_exp2f(d1[1]);
;         ps2 += (f32x2v){s0[r], s0[r + 1]}; ps2 += (f32x2v){s1[r], s1[r + 1]}; }
;     lsum = lsum * alpha + (ps2[0] + ps2[1]); mrun = mnew;
; #pragma unroll
;     for (int r = 0; r < 16; ++r) { o[0][r] *= alpha; o[1][r] *= alpha; }
;     pv_tile(o, Vt, s0, s1, r32, hi);
; template <int MODE> ...
;     ...
;         if (more) { LAS unsigned char* Kn = tb + (cur ^ 1) * 2 * TILEB; tile_st(Kn, kw, tid); tile_st(Kn + TILEB, vw, tid); }
.LBB0_865:
	s_nop 4
	v_max3_f32 v172, v103, v119, v104
	v_max3_f32 v173, v110, v126, v111
	v_max3_f32 v172, v172, v120, v105
	v_max3_f32 v173, v173, v127, v112
	v_max3_f32 v172, v172, v121, v118
	v_max3_f32 v173, v173, v128, v113
	v_max3_f32 v172, v172, v102, v106
	v_max3_f32 v173, v173, v129, v114
	v_max3_f32 v172, v172, v122, v107
	v_max3_f32 v173, v173, v130, v115
	v_max3_f32 v172, v172, v123, v108
	v_max3_f32 v173, v173, v131, v116
	v_max3_f32 v172, v172, v124, v109
	v_max3_f32 v173, v173, v132, v117
	v_max3_f32 v172, v172, v125, v133
	v_max_f32_e32 v172, v172, v173
	v_mov_b32_e32 v173, v172
	v_mov_b32_e32 v186, v172
	s_nop 1
	v_permlane32_swap_b32_e32 v173, v186
	v_max3_f32 v173, v245, v173, v186
	v_cmp_neq_f32_e32 vcc, s96, v173
	s_nop 1
	v_cndmask_b32_e32 v172, 0, v173, vcc
	v_pk_add_f32 v[118:119], v[118:119], v[172:173] op_sel_hi:[1,0] neg_lo:[0,1] neg_hi:[0,1]
	v_pk_add_f32 v[186:187], v[102:103], v[172:173] op_sel_hi:[1,0] neg_lo:[0,1] neg_hi:[0,1]
	v_sub_f32_e32 v189, v245, v172
	v_exp_f32_e32 v102, v118
	v_exp_f32_e32 v103, v119
	v_exp_f32_e32 v118, v186
	v_exp_f32_e32 v119, v187
	v_pk_add_f32 v[120:121], v[120:121], v[172:173] op_sel_hi:[1,0] neg_lo:[0,1] neg_hi:[0,1]
	v_pk_add_f32 v[186:187], v[104:105], v[172:173] op_sel_hi:[1,0] neg_lo:[0,1] neg_hi:[0,1]
	v_pk_add_f32 v[122:123], v[122:123], v[172:173] op_sel_hi:[1,0] neg_lo:[0,1] neg_hi:[0,1]
	v_exp_f32_e32 v104, v120
	v_exp_f32_e32 v105, v121
	v_exp_f32_e32 v120, v186
	v_exp_f32_e32 v121, v187
	v_pk_add_f32 v[186:187], v[106:107], v[172:173] op_sel_hi:[1,0] neg_lo:[0,1] neg_hi:[0,1]
	v_exp_f32_e32 v106, v122
	v_exp_f32_e32 v107, v123
	v_pk_add_f32 v[122:123], v[124:125], v[172:173] op_sel_hi:[1,0] neg_lo:[0,1] neg_hi:[0,1]
	v_pk_add_f32 v[124:125], v[126:127], v[172:173] op_sel_hi:[1,0] neg_lo:[0,1] neg_hi:[0,1]
	v_pk_add_f32 v[126:127], v[128:129], v[172:173] op_sel_hi:[1,0] neg_lo:[0,1] neg_hi:[0,1]
	v_exp_f32_e32 v128, v189
	v_exp_f32_e32 v122, v122
	v_exp_f32_e32 v123, v123
	v_cvt_pk_bf16_f32 v192, v102, v103
	v_pk_mul_f32 v[82:83], v[82:83], v[128:129] op_sel_hi:[1,0]
	v_pk_mul_f32 v[80:81], v[80:81], v[128:129] op_sel_hi:[1,0]
	v_pk_mul_f32 v[78:79], v[78:79], v[128:129] op_sel_hi:[1,0]
	v_pk_mul_f32 v[76:77], v[76:77], v[128:129] op_sel_hi:[1,0]
	v_pk_mul_f32 v[74:75], v[74:75], v[128:129] op_sel_hi:[1,0]
	v_pk_mul_f32 v[72:73], v[72:73], v[128:129] op_sel_hi:[1,0]
	v_pk_mul_f32 v[70:71], v[70:71], v[128:129] op_sel_hi:[1,0]
	v_add3_u32 v129, s11, v188, v237
	ds_read_b128 v[188:191], v129 offset:9216
	ds_read_b128 v[196:199], v129 offset:13824
	v_pk_mul_f32 v[68:69], v[68:69], v[128:129] op_sel_hi:[1,0]
	v_cvt_pk_bf16_f32 v193, v104, v105
	v_cvt_pk_bf16_f32 v194, v106, v107
	v_cvt_pk_bf16_f32 v195, v122, v123
	v_pk_add_f32 v[130:131], v[130:131], v[172:173] op_sel_hi:[1,0] neg_lo:[0,1] neg_hi:[0,1]
	v_pk_add_f32 v[132:133], v[132:133], v[172:173] op_sel_hi:[1,0] neg_lo:[0,1] neg_hi:[0,1]
	s_waitcnt lgkmcnt(1)
	v_mfma_f32_32x32x16_bf16 v[68:83], v[188:191], v[192:195], v[68:83]
	ds_read_b128 v[188:191], v129 offset:9248
	v_exp_f32_e32 v124, v124
	v_exp_f32_e32 v125, v125
	v_exp_f32_e32 v126, v126
	v_exp_f32_e32 v127, v127
	v_exp_f32_e32 v130, v130
	v_exp_f32_e32 v131, v131
	v_exp_f32_e32 v132, v132
	v_exp_f32_e32 v133, v133
	v_pk_mul_f32 v[98:99], v[98:99], v[128:129] op_sel_hi:[1,0]
	v_pk_mul_f32 v[96:97], v[96:97], v[128:129] op_sel_hi:[1,0]
	v_pk_mul_f32 v[94:95], v[94:95], v[128:129] op_sel_hi:[1,0]
	v_pk_mul_f32 v[92:93], v[92:93], v[128:129] op_sel_hi:[1,0]
	v_pk_mul_f32 v[90:91], v[90:91], v[128:129] op_sel_hi:[1,0]
	v_pk_mul_f32 v[88:89], v[88:89], v[128:129] op_sel_hi:[1,0]
	v_pk_mul_f32 v[86:87], v[86:87], v[128:129] op_sel_hi:[1,0]
	v_pk_mul_f32 v[84:85], v[84:85], v[128:129] op_sel_hi:[1,0]
	v_pk_add_f32 v[108:109], v[108:109], v[172:173] op_sel_hi:[1,0] neg_lo:[0,1] neg_hi:[0,1]
	v_exp_f32_e32 v186, v186
	s_waitcnt lgkmcnt(1)
	v_mfma_f32_32x32x16_bf16 v[84:99], v[196:199], v[192:195], v[84:99]
	v_cvt_pk_bf16_f32 v192, v124, v125
	v_cvt_pk_bf16_f32 v193, v126, v127
	v_cvt_pk_bf16_f32 v194, v130, v131
	v_cvt_pk_bf16_f32 v195, v132, v133
	ds_read_b128 v[196:199], v129 offset:13856
	v_exp_f32_e32 v187, v187
	v_exp_f32_e32 v108, v108
	s_waitcnt lgkmcnt(1)
	v_mfma_f32_32x32x16_bf16 v[68:83], v[188:191], v[192:195], v[68:83]
	ds_read_b128 v[188:191], v129 offset:9280
	v_exp_f32_e32 v109, v109
	v_pk_add_f32 v[110:111], v[110:111], v[172:173] op_sel_hi:[1,0] neg_lo:[0,1] neg_hi:[0,1]
	v_pk_add_f32 v[112:113], v[112:113], v[172:173] op_sel_hi:[1,0] neg_lo:[0,1] neg_hi:[0,1]
	v_pk_add_f32 v[114:115], v[114:115], v[172:173] op_sel_hi:[1,0] neg_lo:[0,1] neg_hi:[0,1]
	v_pk_add_f32 v[116:117], v[116:117], v[172:173] op_sel_hi:[1,0] neg_lo:[0,1] neg_hi:[0,1]
	v_exp_f32_e32 v110, v110
	s_waitcnt lgkmcnt(1)
	v_mfma_f32_32x32x16_bf16 v[84:99], v[196:199], v[192:195], v[84:99]
	v_cvt_pk_bf16_f32 v192, v118, v119
	v_cvt_pk_bf16_f32 v193, v120, v121
	v_cvt_pk_bf16_f32 v194, v186, v187
	v_cvt_pk_bf16_f32 v195, v108, v109
	ds_read_b128 v[196:199], v129 offset:13888
	v_exp_f32_e32 v111, v111
	v_exp_f32_e32 v112, v112
	s_waitcnt lgkmcnt(1)
	v_mfma_f32_32x32x16_bf16 v[68:83], v[188:191], v[192:195], v[68:83]
	ds_read_b128 v[188:191], v129 offset:9312
	v_exp_f32_e32 v113, v113
	v_exp_f32_e32 v114, v114
	v_exp_f32_e32 v115, v115
	v_exp_f32_e32 v116, v116
	v_exp_f32_e32 v117, v117
	s_andn2_b64 vcc, exec, s[4:5]
	s_waitcnt lgkmcnt(1)
	v_mfma_f32_32x32x16_bf16 v[84:99], v[196:199], v[192:195], v[84:99]
	v_cvt_pk_bf16_f32 v192, v110, v111
	v_cvt_pk_bf16_f32 v193, v112, v113
	v_cvt_pk_bf16_f32 v194, v114, v115
	v_cvt_pk_bf16_f32 v195, v116, v117
	s_waitcnt lgkmcnt(0)
	s_nop 0
	v_mfma_f32_32x32x16_bf16 v[68:83], v[188:191], v[192:195], v[68:83]
	ds_read_b128 v[188:191], v129 offset:13920
	s_waitcnt lgkmcnt(0)
	v_mfma_f32_32x32x16_bf16 v[84:99], v[188:191], v[192:195], v[84:99]
	s_cbranch_vccnz .LBB0_867
	s_lshl_b32 s4, s10, 1
	s_xor_b32 s4, s4, 2
	s_mulk_i32 s4, 0x2400
	v_add_u32_e32 v129, s4, v243
	s_waitcnt vmcnt(1)
	ds_write_b128 v129, v[150:153]
	s_waitcnt vmcnt(0)
	ds_write_b128 v129, v[154:157] offset:9216
